# itemwait3b: MIX3 hgrn-out loop-top full wait kept only in front of an interleaved RG output item; items without one do not wait for the previous output-store ack; on top of itemwait
# speedup vs baseline: 1.0002x; 1.0002x over previous
.LBB0_91:
	s_cmp_eq_u32 s100, -1
	s_cbranch_scc1 .Lrga_skip
	s_waitcnt vmcnt(0)
	s_lshr_b32 s98, s100, 1
	s_and_b32 s99, s100, 1
	v_mov_b32_e32 v160, s98
	v_mov_b32_e32 v161, s99
	s_cmp_eq_u64 s[4:5], 0
	s_cbranch_scc0 .Lrga_l1
	v_cmp_le_u32_e32 vcc, 0x84, v160
	s_nop 1
	v_cndmask_b32_e64 v162, 0, 1, vcc
	v_mul_u32_u24_e32 v163, 0x84, v162
	v_sub_u32_e32 v160, v160, v163
	s_branch .Lrga_dec
